# cache-policy hints: streaming tile fills of ret_out (s_prev/k/v) and ret_kv marked nt (on top of v38)
# speedup vs baseline: 1.0104x; 1.0104x over previous
.LBB0_691:
	s_or_b64 exec, exec, s[0:1]
	v_lshrrev_b32_e32 v200, 3, v67
	v_mul_u32_u24_e32 v201, v4, v200
	v_and_b32_e32 v202, 7, v67
	v_lshlrev_b32_e32 v201, 1, v201
	v_lshlrev_b32_e32 v202, 4, v202
	v_lshl_add_u32 v201, v6, 1, v201
	v_add_u32_e32 v202, v201, v202
	v_mov_b32_e32 v203, 0
	v_lshl_add_u64 v[204:205], v[0:1], 0, v[202:203]
	v_lshl_add_u64 v[206:207], v[2:3], 0, v[202:203]
	v_lshlrev_b32_e32 v208, 6, v4
	v_mov_b32_e32 v209, 0
	global_load_dwordx4 v[160:163], v[204:205], off nt
	global_load_dwordx4 v[176:179], v[206:207], off nt
	v_lshl_add_u64 v[204:205], v[204:205], 0, v[208:209]
	v_lshl_add_u64 v[206:207], v[206:207], 0, v[208:209]
	global_load_dwordx4 v[164:167], v[204:205], off nt
	global_load_dwordx4 v[180:183], v[206:207], off nt
	v_lshl_add_u64 v[204:205], v[204:205], 0, v[208:209]
	v_lshl_add_u64 v[206:207], v[206:207], 0, v[208:209]
	global_load_dwordx4 v[168:171], v[204:205], off nt
	global_load_dwordx4 v[184:187], v[206:207], off nt
	v_lshl_add_u64 v[204:205], v[204:205], 0, v[208:209]
	v_lshl_add_u64 v[206:207], v[206:207], 0, v[208:209]
	global_load_dwordx4 v[172:175], v[204:205], off nt
	global_load_dwordx4 v[188:191], v[206:207], off nt
	s_mul_i32 s99, s98, 0x9000
	v_mul_u32_u24_e32 v212, 0x14000, v150
	v_add_u32_e32 v212, s99, v212
	v_mul_u32_u24_e32 v210, 0x90, v200
	v_and_b32_e32 v211, 7, v67
	v_lshl_add_u32 v210, v211, 4, v210
	v_add_u32_e32 v210, v210, v212
	v_and_b32_e32 v213, 0x5f, v67
	v_mul_u32_u24_e32 v213, 0x90, v213
	v_bfe_u32 v211, v67, 5, 1
	v_lshl_add_u32 v213, v211, 4, v213
	v_add_u32_e32 v213, v213, v212
	v_ashrrev_i32_e32 v214, 1, v67
	v_and_b32_e32 v214, 0xffc0, v214
	v_and_b32_e32 v215, 31, v67
	v_or_b32_e32 v214, v214, v215
	v_mul_u32_u24_e32 v214, 0x90, v214
	v_lshl_add_u32 v214, v211, 4, v214
	v_add_u32_e32 v214, v214, v212
	v_add_u32_e32 v214, 0x4800, v214
	s_waitcnt vmcnt(0)
	ds_write_b128 v210, v[160:163]
	ds_write_b128 v210, v[164:167] offset:4608
	ds_write_b128 v210, v[168:171] offset:9216
	ds_write_b128 v210, v[172:175] offset:13824
	ds_write_b128 v210, v[176:179] offset:18432
	ds_write_b128 v210, v[180:183] offset:23040
	ds_write_b128 v210, v[184:187] offset:27648
	ds_write_b128 v210, v[188:191] offset:32256
	s_waitcnt lgkmcnt(0)
	s_barrier
	v_and_b32_e32 v18, 0x5f, v67
	v_and_b32_e32 v5, 31, v67
	v_ashrrev_i32_e32 v10, 1, v67
	v_mul_u32_u24_e32 v7, v4, v18
	v_lshlrev_b32_e32 v64, 1, v7
	v_and_or_b32 v102, v10, s3, v5
	v_bfe_u32 v71, v67, 5, 1
	v_lshl_add_u64 v[8:9], v[0:1], 0, v[64:65]
	v_lshlrev_b32_e32 v64, 1, v6
	v_or_b32_e32 v66, 32, v102
	v_lshl_add_u64 v[6:7], v[8:9], 0, v[64:65]
	v_lshlrev_b32_e32 v14, 4, v71
	v_mov_b32_e32 v15, v65
	v_mad_i64_i32 v[10:11], s[0:1], v4, v102, 0
	v_mad_i64_i32 v[16:17], s[0:1], v4, v66, 0
	v_lshl_add_u64 v[92:93], v[6:7], 0, v[14:15]
	v_lshl_add_u64 v[10:11], v[10:11], 1, v[2:3]
	v_lshl_add_u64 v[2:3], v[16:17], 1, v[2:3]
	ds_read_b128 v[6:9], v213
	v_lshl_add_u64 v[2:3], v[2:3], 0, v[64:65]
	v_lshl_add_u64 v[96:97], v[2:3], 0, v[14:15]
	v_or_b32_e32 v2, 32, v18
	v_lshl_add_u64 v[10:11], v[10:11], 0, v[64:65]
	v_mul_u32_u24_e32 v2, v4, v2
	v_lshl_add_u64 v[94:95], v[10:11], 0, v[14:15]
	v_mov_b32_e32 v3, v65
	v_lshlrev_b32_e32 v2, 1, v2
	ds_read_b128 v[10:13], v214
	ds_read_b128 v[72:75], v214 offset:4608
	v_lshl_add_u64 v[0:1], v[0:1], 0, v[2:3]
	v_lshl_add_u64 v[0:1], v[0:1], 0, v[64:65]
	v_lshl_add_u64 v[100:101], v[0:1], 0, v[14:15]
	ds_read_b128 v[76:79], v213 offset:32
	ds_read_b128 v[80:83], v214 offset:32
	ds_read_b128 v[0:3], v213 offset:4608
	ds_read_b128 v[84:87], v214 offset:4640
	ds_read_b128 v[88:91], v213 offset:4640
	v_lshlrev_b32_e32 v64, 7, v67
	v_and_b32_e32 v64, 0x2000, v64
	v_ashrrev_i32_e32 v69, 31, v68
	v_lshl_or_b32 v64, v71, 9, v64
	v_lshlrev_b64 v[68:69], 15, v[68:69]
	v_or_b32_e32 v71, 0x800, v64
	v_or_b32_e32 v103, 0x880, v64
	v_or_b32_e32 v104, 0x900, v64
	v_or_b32_e32 v105, 0x980, v64
	v_or_b32_e32 v106, 0xc00, v64
	v_or_b32_e32 v107, 0xc80, v64
	v_lshl_add_u64 v[68:69], s[88:89], 0, v[68:69]
	v_ashrrev_i32_e32 v67, 31, v66
	v_add_u32_e32 v70, 0x8000, v70
	s_waitcnt lgkmcnt(6)
	v_mfma_f32_32x32x16_bf16 v[48:63], v[6:9], v[10:13], 0
	s_waitcnt lgkmcnt(5)
	v_mfma_f32_32x32x16_bf16 v[32:47], v[6:9], v[72:75], 0
	s_waitcnt lgkmcnt(2)
	v_mfma_f32_32x32x16_bf16 v[16:31], v[0:3], v[10:13], 0
	v_mfma_f32_32x32x16_bf16 v[0:15], v[0:3], v[72:75], 0
	ds_read_b128 v[72:75], v213 offset:64
	v_mfma_f32_32x32x16_bf16 v[48:63], v[76:79], v[80:83], v[48:63]
	s_waitcnt lgkmcnt(2)
	v_mfma_f32_32x32x16_bf16 v[32:47], v[76:79], v[84:87], v[32:47]
	ds_read_b128 v[76:79], v214 offset:64
	s_waitcnt lgkmcnt(2)
	v_mfma_f32_32x32x16_bf16 v[16:31], v[88:91], v[80:83], v[16:31]
	v_mfma_f32_32x32x16_bf16 v[0:15], v[88:91], v[84:87], v[0:15]
	ds_read_b128 v[80:83], v214 offset:4672
	ds_read_b128 v[84:87], v213 offset:96
	ds_read_b128 v[88:91], v214 offset:96
	s_nop 0
	ds_read_b128 v[92:95], v213 offset:4672
	s_nop 0
	ds_read_b128 v[96:99], v214 offset:4704
	s_waitcnt lgkmcnt(4)
	v_mfma_f32_32x32x16_bf16 v[32:47], v[72:75], v[80:83], v[32:47]
	v_mfma_f32_32x32x16_bf16 v[48:63], v[72:75], v[76:79], v[48:63]
	ds_read_b128 v[72:75], v213 offset:4704
	v_add_u32_e32 v100, v107, v102
	v_ashrrev_i32_e32 v101, 31, v100
	s_waitcnt lgkmcnt(3)
	v_mfma_f32_32x32x16_bf16 v[48:63], v[84:87], v[88:91], v[48:63]
	s_waitcnt lgkmcnt(2)
	v_mfma_f32_32x32x16_bf16 v[16:31], v[92:95], v[76:79], v[16:31]
	v_mfma_f32_32x32x16_bf16 v[0:15], v[92:95], v[80:83], v[0:15]
	s_waitcnt lgkmcnt(1)
	v_mfma_f32_32x32x16_bf16 v[32:47], v[84:87], v[96:99], v[32:47]
	s_waitcnt lgkmcnt(0)
	v_mfma_f32_32x32x16_bf16 v[16:31], v[72:75], v[88:91], v[16:31]
	v_mfma_f32_32x32x16_bf16 v[0:15], v[72:75], v[96:99], v[0:15]
	v_and_b32_e32 v216, 63, v151
	v_lshrrev_b32_e32 v217, 6, v151
	v_and_b32_e32 v218, 31, v216
	v_lshrrev_b32_e32 v219, 5, v216
	v_mul_u32_u24_e32 v220, 0x14000, v150
	v_lshl_add_u32 v220, v217, 11, v220
	v_add_u32_e32 v220, 0x12000, v220
	v_lshlrev_b32_e32 v221, 9, v219
	v_lshl_add_u32 v221, v218, 1, v221
	v_add_u32_e32 v221, v221, v220
	v_lshl_add_u32 v222, v216, 4, v220
	v_and_b32_e32 v224, 1, v217
	v_lshlrev_b32_e32 v224, 6, v224
	v_lshrrev_b32_e32 v223, 3, v216
	v_add_u32_e32 v224, v224, v223
	v_lshlrev_b32_e32 v224, 8, v224
	v_lshrrev_b32_e32 v223, 1, v217
	v_lshl_add_u32 v224, v223, 7, v224
	v_and_b32_e32 v223, 7, v216
	v_lshl_add_u32 v224, v223, 4, v224
	v_mov_b32_e32 v225, 0
	v_lshl_add_u64 v[226:227], v[68:69], 0, v[224:225]
	v_mov_b32_e32 v208, 0x800
	v_mov_b32_e32 v209, 0
	s_nop 7
	v_cvt_pk_bf16_f32 v176, v48, s0
	ds_write_b16 v221, v176
	v_cvt_pk_bf16_f32 v177, v49, s0
	ds_write_b16 v221, v177 offset:128
	v_cvt_pk_bf16_f32 v178, v50, s0
	ds_write_b16 v221, v178 offset:256
	v_cvt_pk_bf16_f32 v179, v51, s0
	ds_write_b16 v221, v179 offset:384
	v_cvt_pk_bf16_f32 v180, v32, s0
	ds_write_b16 v221, v180 offset:64
	v_cvt_pk_bf16_f32 v181, v33, s0
	ds_write_b16 v221, v181 offset:192
	v_cvt_pk_bf16_f32 v182, v34, s0
	ds_write_b16 v221, v182 offset:320
	v_cvt_pk_bf16_f32 v183, v35, s0
	ds_write_b16 v221, v183 offset:448
	s_waitcnt lgkmcnt(0)
	ds_read_b128 v[200:203], v222
	v_cvt_pk_bf16_f32 v176, v52, s0
	ds_write_b16 v221, v176 offset:1024
	v_cvt_pk_bf16_f32 v177, v53, s0
	ds_write_b16 v221, v177 offset:1152
	v_cvt_pk_bf16_f32 v178, v54, s0
	ds_write_b16 v221, v178 offset:1280
	v_cvt_pk_bf16_f32 v179, v55, s0
	ds_write_b16 v221, v179 offset:1408
	v_cvt_pk_bf16_f32 v180, v36, s0
	ds_write_b16 v221, v180 offset:1088
	v_cvt_pk_bf16_f32 v181, v37, s0
	ds_write_b16 v221, v181 offset:1216
	v_cvt_pk_bf16_f32 v182, v38, s0
	ds_write_b16 v221, v182 offset:1344
	v_cvt_pk_bf16_f32 v183, v39, s0
	ds_write_b16 v221, v183 offset:1472
	s_waitcnt lgkmcnt(0)
	ds_read_b128 v[204:207], v222 offset:1024
	global_store_dwordx4 v[226:227], v[200:203], off
	v_lshl_add_u64 v[226:227], v[226:227], 0, v[208:209]
	v_cvt_pk_bf16_f32 v176, v56, s0
	ds_write_b16 v221, v176
	v_cvt_pk_bf16_f32 v177, v57, s0
	ds_write_b16 v221, v177 offset:128
	v_cvt_pk_bf16_f32 v178, v58, s0
	ds_write_b16 v221, v178 offset:256
	v_cvt_pk_bf16_f32 v179, v59, s0
	ds_write_b16 v221, v179 offset:384
	v_cvt_pk_bf16_f32 v180, v40, s0
	ds_write_b16 v221, v180 offset:64
	v_cvt_pk_bf16_f32 v181, v41, s0
	ds_write_b16 v221, v181 offset:192
	v_cvt_pk_bf16_f32 v182, v42, s0
	ds_write_b16 v221, v182 offset:320
	v_cvt_pk_bf16_f32 v183, v43, s0
	ds_write_b16 v221, v183 offset:448
	s_waitcnt lgkmcnt(0)
	ds_read_b128 v[200:203], v222
	global_store_dwordx4 v[226:227], v[204:207], off
	v_lshl_add_u64 v[226:227], v[226:227], 0, v[208:209]
	v_cvt_pk_bf16_f32 v176, v60, s0
	ds_write_b16 v221, v176 offset:1024
	v_cvt_pk_bf16_f32 v177, v61, s0
	ds_write_b16 v221, v177 offset:1152
	v_cvt_pk_bf16_f32 v178, v62, s0
	ds_write_b16 v221, v178 offset:1280
	v_cvt_pk_bf16_f32 v179, v63, s0
	ds_write_b16 v221, v179 offset:1408
	v_cvt_pk_bf16_f32 v180, v44, s0
	ds_write_b16 v221, v180 offset:1088
	v_cvt_pk_bf16_f32 v181, v45, s0
	ds_write_b16 v221, v181 offset:1216
	v_cvt_pk_bf16_f32 v182, v46, s0
	ds_write_b16 v221, v182 offset:1344
	v_cvt_pk_bf16_f32 v183, v47, s0
	ds_write_b16 v221, v183 offset:1472
	s_waitcnt lgkmcnt(0)
	ds_read_b128 v[204:207], v222 offset:1024
	global_store_dwordx4 v[226:227], v[200:203], off
	v_lshl_add_u64 v[226:227], v[226:227], 0, v[208:209]
	v_cvt_pk_bf16_f32 v176, v16, s0
	ds_write_b16 v221, v176
	v_cvt_pk_bf16_f32 v177, v17, s0
	ds_write_b16 v221, v177 offset:128
	v_cvt_pk_bf16_f32 v178, v18, s0
	ds_write_b16 v221, v178 offset:256
	v_cvt_pk_bf16_f32 v179, v19, s0
	ds_write_b16 v221, v179 offset:384
	v_cvt_pk_bf16_f32 v180, v0, s0
	ds_write_b16 v221, v180 offset:64
	v_cvt_pk_bf16_f32 v181, v1, s0
	ds_write_b16 v221, v181 offset:192
	v_cvt_pk_bf16_f32 v182, v2, s0
	ds_write_b16 v221, v182 offset:320
	v_cvt_pk_bf16_f32 v183, v3, s0
	ds_write_b16 v221, v183 offset:448
	s_waitcnt lgkmcnt(0)
	ds_read_b128 v[200:203], v222
	global_store_dwordx4 v[226:227], v[204:207], off
	v_lshl_add_u64 v[226:227], v[226:227], 0, v[208:209]
	v_cvt_pk_bf16_f32 v176, v20, s0
	ds_write_b16 v221, v176 offset:1024
	v_cvt_pk_bf16_f32 v177, v21, s0
	ds_write_b16 v221, v177 offset:1152
	v_cvt_pk_bf16_f32 v178, v22, s0
	ds_write_b16 v221, v178 offset:1280
	v_cvt_pk_bf16_f32 v179, v23, s0
	ds_write_b16 v221, v179 offset:1408
	v_cvt_pk_bf16_f32 v180, v4, s0
	ds_write_b16 v221, v180 offset:1088
	v_cvt_pk_bf16_f32 v181, v5, s0
	ds_write_b16 v221, v181 offset:1216
	v_cvt_pk_bf16_f32 v182, v6, s0
	ds_write_b16 v221, v182 offset:1344
	v_cvt_pk_bf16_f32 v183, v7, s0
	ds_write_b16 v221, v183 offset:1472
	s_waitcnt lgkmcnt(0)
	ds_read_b128 v[204:207], v222 offset:1024
	global_store_dwordx4 v[226:227], v[200:203], off
	v_lshl_add_u64 v[226:227], v[226:227], 0, v[208:209]
	v_cvt_pk_bf16_f32 v176, v24, s0
	ds_write_b16 v221, v176
	v_cvt_pk_bf16_f32 v177, v25, s0
	ds_write_b16 v221, v177 offset:128
	v_cvt_pk_bf16_f32 v178, v26, s0
	ds_write_b16 v221, v178 offset:256
	v_cvt_pk_bf16_f32 v179, v27, s0
	ds_write_b16 v221, v179 offset:384
	v_cvt_pk_bf16_f32 v180, v8, s0
	ds_write_b16 v221, v180 offset:64
	v_cvt_pk_bf16_f32 v181, v9, s0
	ds_write_b16 v221, v181 offset:192
	v_cvt_pk_bf16_f32 v182, v10, s0
	ds_write_b16 v221, v182 offset:320
	v_cvt_pk_bf16_f32 v183, v11, s0
	ds_write_b16 v221, v183 offset:448
	s_waitcnt lgkmcnt(0)
	ds_read_b128 v[200:203], v222
	global_store_dwordx4 v[226:227], v[204:207], off
	v_lshl_add_u64 v[226:227], v[226:227], 0, v[208:209]
	v_cvt_pk_bf16_f32 v176, v28, s0
	ds_write_b16 v221, v176 offset:1024
	v_cvt_pk_bf16_f32 v177, v29, s0
	ds_write_b16 v221, v177 offset:1152
	v_cvt_pk_bf16_f32 v178, v30, s0
	ds_write_b16 v221, v178 offset:1280
	v_cvt_pk_bf16_f32 v179, v31, s0
	ds_write_b16 v221, v179 offset:1408
	v_cvt_pk_bf16_f32 v180, v12, s0
	ds_write_b16 v221, v180 offset:1088
	v_cvt_pk_bf16_f32 v181, v13, s0
	ds_write_b16 v221, v181 offset:1216
	v_cvt_pk_bf16_f32 v182, v14, s0
	ds_write_b16 v221, v182 offset:1344
	v_cvt_pk_bf16_f32 v183, v15, s0
	ds_write_b16 v221, v183 offset:1472
	s_waitcnt lgkmcnt(0)
	ds_read_b128 v[204:207], v222 offset:1024
	global_store_dwordx4 v[226:227], v[200:203], off
	v_lshl_add_u64 v[226:227], v[226:227], 0, v[208:209]
	s_waitcnt lgkmcnt(0)
	global_store_dwordx4 v[226:227], v[204:207], off
	s_add_i32 s0, s4, 0x200
	s_xor_b32 s98, s98, 1
	s_cmpk_gt_i32 s4, 0x61f
	s_mov_b32 s4, s0
	s_cbranch_scc1 .LBB0_696

.LBB0_913:
	s_or_b64 exec, exec, s[0:1]
	v_readlane_b32 s20, v253, 13
	v_readlane_b32 s21, v253, 14
	v_ashrrev_i32_e32 v201, 31, v10
	v_mov_b32_e32 v200, v10
	v_lshlrev_b64 v[200:201], 15, v[200:201]
	v_lshlrev_b32_e32 v202, 4, v172
	v_mov_b32_e32 v203, 0
	v_lshl_add_u64 v[200:201], s[20:21], 0, v[200:201]
	v_lshl_add_u64 v[232:233], v[200:201], 0, v[202:203]
	s_mov_b64 s[20:21], 0x1000
	global_load_dwordx4 v[200:203], v[232:233], off nt
	v_lshl_add_u64 v[232:233], v[232:233], 0, s[20:21]
	global_load_dwordx4 v[204:207], v[232:233], off nt
	v_lshl_add_u64 v[232:233], v[232:233], 0, s[20:21]
	global_load_dwordx4 v[208:211], v[232:233], off nt
	v_lshl_add_u64 v[232:233], v[232:233], 0, s[20:21]
	global_load_dwordx4 v[212:215], v[232:233], off nt
	v_lshl_add_u64 v[232:233], v[232:233], 0, s[20:21]
	global_load_dwordx4 v[216:219], v[232:233], off nt
	v_lshl_add_u64 v[232:233], v[232:233], 0, s[20:21]
	global_load_dwordx4 v[220:223], v[232:233], off nt
	v_lshl_add_u64 v[232:233], v[232:233], 0, s[20:21]
	global_load_dwordx4 v[224:227], v[232:233], off nt
	v_lshl_add_u64 v[232:233], v[232:233], 0, s[20:21]
	global_load_dwordx4 v[228:231], v[232:233], off nt
	v_and_b32_e32 v169, 3, v2
	v_cvt_f32_ubyte0_e32 v0, v169
	v_sub_f32_e32 v0, 0xc0a00000, v0
	v_cmp_gt_f32_e32 vcc, s34, v0
	s_mov_b32 s0, 0x3f2aaaab
	v_and_b32_e32 v113, 31, v172
	v_cndmask_b32_e32 v2, 0, v187, vcc
	v_add_f32_e32 v0, v0, v2
	v_exp_f32_e32 v0, v0
	v_cndmask_b32_e32 v2, 0, v188, vcc
	v_ashrrev_i32_e32 v191, 1, v172
	v_and_or_b32 v193, v191, 32, v113
	v_ldexp_f32 v11, v0, v2
	v_sub_f32_e32 v0, 1.0, v11
	v_add_f32_e32 v2, -1.0, v0
	v_sub_f32_e32 v3, v2, v0
	v_add_f32_e32 v3, 1.0, v3
	v_sub_f32_e64 v2, -v11, v2
	v_add_f32_e32 v4, v2, v3
	v_frexp_mant_f32_e32 v5, v0
	v_cvt_f64_f32_e32 v[2:3], v0
	v_frexp_exp_i32_f64_e32 v2, v[2:3]
	v_cmp_gt_f32_e32 vcc, s0, v5
	v_readlane_b32 s0, v252, 55
	v_readlane_b32 s1, v252, 56
	v_subbrev_co_u32_e32 v111, vcc, 0, v2, vcc
	v_sub_u32_e32 v2, 0, v111
	v_ldexp_f32 v0, v0, v2
	v_ldexp_f32 v2, v4, v2
	v_add_f32_e32 v4, -1.0, v0
	v_add_f32_e32 v3, 1.0, v4
	v_sub_f32_e32 v3, v0, v3
	v_add_f32_e32 v5, v2, v3
	v_add_f32_e32 v3, 1.0, v0
	v_add_f32_e32 v6, -1.0, v3
	v_sub_f32_e32 v0, v0, v6
	v_add_f32_e32 v0, v2, v0
	v_add_f32_e32 v114, v3, v0
	v_rcp_f32_e32 v116, v114
	v_sub_f32_e32 v2, v114, v3
	v_add_f32_e32 v3, v4, v5
	v_sub_f32_e32 v115, v0, v2
	v_mul_f32_e32 v117, v3, v116
	v_mul_f32_e32 v18, v114, v117
	v_sub_f32_e32 v0, v3, v4
	v_fma_f32 v4, v117, v114, -v18
	v_fmac_f32_e32 v4, v117, v115
	v_add_f32_e32 v2, v18, v4
	v_sub_f32_e32 v19, v3, v2
	v_sub_f32_e32 v0, v5, v0
	v_pk_add_f32 v[6:7], v[2:3], v[18:19] neg_lo:[0,1] neg_hi:[0,1]
	v_mov_b32_e32 v5, v2
	v_pk_add_f32 v[2:3], v[6:7], v[4:5] neg_lo:[0,1] neg_hi:[0,1]
	v_bfe_u32 v173, v172, 5, 1
	v_add_f32_e32 v0, v0, v3
	v_add_f32_e32 v18, v2, v0
	v_add_u32_e32 v2, v112, v193
	v_ashrrev_i32_e32 v3, 31, v2
	v_lshlrev_b64 v[174:175], 10, v[2:3]
	v_lshl_add_u64 v[2:3], s[0:1], 0, v[174:175]
	v_lshlrev_b32_e32 v0, 8, v169
	v_lshl_add_u64 v[2:3], v[2:3], 0, v[0:1]
	v_lshlrev_b32_e32 v32, 4, v173
	v_mov_b32_e32 v33, v1
	v_lshl_add_u64 v[2:3], v[2:3], 0, v[32:33]
	global_load_dwordx4 v[78:81], v[2:3], off
	global_load_dwordx4 v[74:77], v[2:3], off offset:32
	global_load_dwordx4 v[70:73], v[2:3], off offset:64
	global_load_dwordx4 v[66:69], v[2:3], off offset:96
	global_load_dwordx4 v[62:65], v[2:3], off offset:128
	global_load_dwordx4 v[58:61], v[2:3], off offset:160
	global_load_dwordx4 v[54:57], v[2:3], off offset:192
	global_load_dwordx4 v[50:53], v[2:3], off offset:224
	v_add_u32_e32 v2, v112, v113
	v_ashrrev_i32_e32 v3, 31, v2
	v_readlane_b32 s20, v252, 53
	v_lshlrev_b64 v[2:3], 10, v[2:3]
	v_readlane_b32 s21, v252, 54
	v_and_b32_e32 v192, 0xffffffc0, v191
	v_lshlrev_b32_e32 v16, 1, v16
	v_mov_b32_e32 v17, v1
	v_lshlrev_b32_e32 v20, 3, v173
	v_mov_b32_e32 v21, v1
	v_lshl_add_u64 v[2:3], s[20:21], 0, v[2:3]
	v_or_b32_e32 v110, v192, v113
	v_lshl_add_u64 v[12:13], v[12:13], 0, v[16:17]
	v_mov_b64_e32 v[248:249], v[12:13]
	v_lshl_add_u64 v[2:3], v[2:3], 0, v[0:1]
	v_lshl_add_u64 v[12:13], v[12:13], 0, v[20:21]
	v_mad_i64_i32 v[16:17], s[0:1], v14, v110, 0
	v_lshl_add_u64 v[22:23], v[2:3], 0, v[32:33]
	v_lshl_add_u64 v[16:17], v[16:17], 1, v[12:13]
	v_lshrrev_b32_e32 v232, 4, v172
	v_add_u32_e32 v232, v112, v232
	v_ashrrev_i32_e32 v233, 31, v232
	v_lshlrev_b64 v[232:233], 10, v[232:233]
	v_and_b32_e32 v254, 15, v172
	v_lshlrev_b32_e32 v254, 4, v254
	v_mov_b32_e32 v255, 0
	v_lshl_add_u64 v[232:233], s[20:21], 0, v[232:233]
	v_lshl_add_u64 v[232:233], v[232:233], 0, v[0:1]
	v_lshl_add_u64 v[232:233], v[232:233], 0, v[254:255]
	s_mov_b64 s[20:21], 0x4000
	global_load_dwordx4 v[46:49], v[232:233], off nt
	v_lshl_add_u64 v[232:233], v[232:233], 0, s[20:21]
	global_load_dwordx4 v[42:45], v[232:233], off nt
	v_lshl_add_u64 v[232:233], v[232:233], 0, s[20:21]
	global_load_dwordx4 v[38:41], v[232:233], off nt
	v_lshl_add_u64 v[232:233], v[232:233], 0, s[20:21]
	global_load_dwordx4 v[28:31], v[232:233], off nt
	v_mul_u32_u24_e32 v242, 0x90, v110
	v_add3_u32 v242, v242, v20, v182
	v_add_u32_e32 v242, 0xd400, v242
	v_add_u32_e32 v243, 0x1200, v242
	v_lshrrev_b32_e32 v246, 3, v172
	v_mad_i64_i32 v[244:245], s[0:1], v14, v246, 0
	v_and_b32_e32 v246, 7, v172
	v_lshlrev_b32_e32 v246, 4, v246
	v_mov_b32_e32 v247, 0
	v_lshl_add_u64 v[244:245], v[244:245], 1, v[248:249]
	v_lshl_add_u64 v[244:245], v[244:245], 0, v[246:247]
	v_lshlrev_b32_e32 v246, 6, v14
	global_load_dwordx4 v[94:97], v[244:245], off nt
	v_lshl_add_u64 v[244:245], v[244:245], 0, v[246:247]
	global_load_dwordx4 v[90:93], v[244:245], off nt
	v_lshl_add_u64 v[244:245], v[244:245], 0, v[246:247]
	global_load_dwordx4 v[86:89], v[244:245], off nt
	v_lshl_add_u64 v[244:245], v[244:245], 0, v[246:247]
	global_load_dwordx4 v[82:85], v[244:245], off nt
	v_lshrrev_b32_e32 v244, 4, v172
	v_add_u32_e32 v244, v112, v244
	v_ashrrev_i32_e32 v245, 31, v244
	v_lshlrev_b64 v[244:245], 11, v[244:245]
	v_lshlrev_b32_e32 v246, 8, v169
	v_mov_b32_e32 v247, 0
	v_lshl_add_u64 v[244:245], s[10:11], 0, v[244:245]
	v_lshl_add_u64 v[244:245], v[244:245], 0, v[246:247]
	v_and_b32_e32 v246, 15, v172
	v_lshlrev_b32_e32 v246, 4, v246
	v_lshl_add_u64 v[244:245], v[244:245], 0, v[246:247]
	v_mov_b32_e32 v246, 0x8000
	global_load_dwordx4 v[34:37], v[244:245], off
	v_lshl_add_u64 v[244:245], v[244:245], 0, v[246:247]
	global_load_dwordx4 v[106:109], v[244:245], off
	v_lshl_add_u64 v[244:245], v[244:245], 0, v[246:247]
	global_load_dwordx4 v[102:105], v[244:245], off
	v_lshl_add_u64 v[244:245], v[244:245], 0, v[246:247]
	global_load_dwordx4 v[98:101], v[244:245], off
	v_add_f32_e32 v15, v19, v18
	v_mul_f32_e32 v118, v116, v15
	v_mul_f32_e32 v12, v114, v118
	v_fma_f32 v16, v118, v114, -v12
	v_fmac_f32_e32 v16, v118, v115
	v_sub_f32_e32 v13, v19, v15
	v_add_f32_e32 v14, v12, v16
	v_add_f32_e32 v20, v18, v13
	v_sub_f32_e32 v13, v15, v14
	v_pk_add_f32 v[18:19], v[14:15], v[12:13] neg_lo:[0,1] neg_hi:[0,1]
	v_mov_b32_e32 v17, v14
	v_pk_add_f32 v[14:15], v[18:19], v[16:17] neg_lo:[0,1] neg_hi:[0,1]
	s_mov_b32 s0, 0x3f317218
	v_add_f32_e32 v12, v20, v15
	v_add_f32_e32 v12, v14, v12
	v_add_f32_e32 v12, v13, v12
	v_add_f32_e32 v13, v117, v118
	v_sub_f32_e32 v14, v13, v117
	v_mul_f32_e32 v12, v116, v12
	v_sub_f32_e32 v14, v118, v14
	v_add_f32_e32 v14, v14, v12
	v_add_f32_e32 v16, v13, v14
	v_mul_f32_e32 v17, v16, v16
	v_fmamk_f32 v12, v17, 0x3e9b6dac, v185
	v_fmaak_f32 v171, v17, v12, 0x3f2aaada
	v_cvt_f32_i32_e32 v12, v111
	v_sub_f32_e32 v13, v16, v13
	v_sub_f32_e32 v13, v14, v13
	v_ldexp_f32 v18, v13, 1
	v_mul_f32_e32 v13, v16, v17
	v_ldexp_f32 v15, v16, 1
	v_pk_mul_f32 v[16:17], v[12:13], v[170:171]
	v_cmp_nlt_f32_e32 vcc, 1.0, v11
	v_fma_f32 v14, v12, s0, -v16
	v_fmac_f32_e32 v14, 0xb102e308, v12
	v_pk_add_f32 v[12:13], v[16:17], v[14:15]
	s_mov_b32 s0, 0x33800000
	v_sub_f32_e32 v15, v13, v15
	v_sub_f32_e32 v15, v17, v15
	v_add_f32_e32 v19, v18, v15
	v_mov_b32_e32 v18, v16
	v_pk_add_f32 v[16:17], v[12:13], v[16:17] neg_lo:[0,1] neg_hi:[0,1]
	v_pk_add_f32 v[20:21], v[12:13], v[18:19]
	v_mov_b32_e32 v15, v12
	v_mov_b32_e32 v17, v21
	v_pk_add_f32 v[22:23], v[14:15], v[16:17] neg_lo:[0,1] neg_hi:[0,1]
	v_pk_add_f32 v[14:15], v[14:15], v[16:17]
	v_mov_b32_e32 v18, v19
	v_pk_add_f32 v[16:17], v[14:15], v[12:13] op_sel:[1,0] op_sel_hi:[0,1] neg_lo:[0,1] neg_hi:[0,1]
	v_pk_add_f32 v[114:115], v[20:21], v[16:17] op_sel_hi:[1,0] neg_lo:[0,1] neg_hi:[0,1]
	v_mov_b32_e32 v20, v21
	v_mov_b32_e32 v21, v15
	v_pk_mov_b32 v[16:17], v[12:13], v[16:17] op_sel:[1,0]
	v_mov_b32_e32 v19, v12
	v_pk_add_f32 v[16:17], v[20:21], v[16:17] neg_lo:[0,1] neg_hi:[0,1]
	v_mov_b32_e32 v114, v22
	v_pk_add_f32 v[12:13], v[18:19], v[16:17] neg_lo:[0,1] neg_hi:[0,1]
	v_mov_b32_e32 v23, v15
	v_pk_add_f32 v[16:17], v[114:115], v[12:13]
	v_lshlrev_b32_e32 v171, 2, v173
	v_pk_add_f32 v[18:19], v[16:17], v[16:17] op_sel:[0,1] op_sel_hi:[1,0]
	v_ashrrev_i32_e32 v111, 31, v110
	v_pk_add_f32 v[14:15], v[14:15], v[18:19] op_sel:[1,0] op_sel_hi:[0,1]
	v_mov_b32_e32 v17, v14
	v_pk_add_f32 v[20:21], v[16:17], v[22:23] neg_lo:[0,1] neg_hi:[0,1]
	v_mov_b32_e32 v13, v18
	v_sub_f32_e32 v15, v16, v20
	v_pk_add_f32 v[12:13], v[12:13], v[20:21] neg_lo:[0,1] neg_hi:[0,1]
	v_sub_f32_e32 v15, v22, v15
	v_add_f32_e32 v12, v12, v15
	v_add_f32_e32 v12, v12, v13
	v_add_f32_e32 v12, v14, v12
	v_cndmask_b32_e32 v12, v189, v12, vcc
	v_cmp_neq_f32_e32 vcc, 1.0, v11
	s_nop 1
	v_cndmask_b32_e32 v12, v190, v12, vcc
	v_cmp_gt_f32_e32 vcc, s0, v11
	v_readlane_b32 s0, v253, 13
	v_readlane_b32 s1, v253, 14
	v_cndmask_b32_e64 v11, v12, -v11, vcc
	v_mul_f32_e32 v194, 0x3fb8aa3b, v11
	v_ashrrev_i32_e32 v11, 31, v10
	v_lshlrev_b64 v[10:11], 15, v[10:11]
	v_lshl_add_u64 v[154:155], s[0:1], 0, v[10:11]
	s_waitcnt vmcnt(0)
	v_lshrrev_b32_e32 v232, 4, v172
	v_and_b32_e32 v233, 15, v172
	v_mul_u32_u24_e32 v232, 0x110, v232
	v_lshl_add_u32 v232, v233, 4, v232
	v_add_u32_e32 v232, v232, v182
	v_mul_u32_u24_e32 v241, 0x110, v113
	v_add3_u32 v241, v241, v32, v182
	v_add_u32_e32 v232, 0x9000, v232
	v_add_u32_e32 v241, 0x9000, v241
	ds_write_b128 v232, v[46:49]
	ds_write_b128 v232, v[42:45] offset:4352
	ds_write_b128 v232, v[38:41] offset:8704
	ds_write_b128 v232, v[28:31] offset:13056
	v_lshrrev_b32_e32 v233, 3, v172
	v_and_b32_e32 v244, 7, v172
	v_mul_u32_u24_e32 v233, 0x90, v233
	v_lshl_add_u32 v233, v244, 4, v233
	v_add_u32_e32 v233, v233, v182
	v_add_u32_e32 v233, 0xd400, v233
	ds_write_b128 v233, v[94:97]
	ds_write_b128 v233, v[90:93] offset:4608
	ds_write_b128 v233, v[86:89] offset:9216
	ds_write_b128 v233, v[82:85] offset:13824
	s_waitcnt lgkmcnt(0)
	s_barrier
	ds_read_b128 v[6:9], v241
	ds_read_b128 v[46:49], v241 offset:32
	ds_read_b128 v[42:45], v241 offset:64
	ds_read_b128 v[38:41], v241 offset:96
	ds_read_b128 v[28:31], v241 offset:128
	ds_read_b128 v[2:5], v241 offset:160
	ds_read_b128 v[24:27], v241 offset:192
	ds_read_b128 v[150:153], v241 offset:224
	s_waitcnt lgkmcnt(0)
	v_mfma_f32_32x32x16_bf16 v[8:23], v[6:9], v[78:81], 0
	v_or_b32_e32 v195, 32, v113
	v_lshlrev_b64 v[6:7], 8, v[110:111]
	v_lshl_add_u64 v[6:7], v[154:155], 0, v[6:7]
	v_lshl_add_u64 v[6:7], v[6:7], 0, v[32:33]
	s_nop 0
	v_mfma_f32_32x32x16_bf16 v[8:23], v[46:49], v[74:77], v[8:23]
	s_nop 0
	v_mfma_f32_32x32x16_bf16 v[8:23], v[42:45], v[70:73], v[8:23]
	s_nop 0
	v_mfma_f32_32x32x16_bf16 v[8:23], v[38:41], v[66:69], v[8:23]
	s_nop 0
	v_mfma_f32_32x32x16_bf16 v[8:23], v[28:31], v[62:65], v[8:23]
	v_add_u32_e32 v28, v112, v195
	v_ashrrev_i32_e32 v29, 31, v28
	v_lshlrev_b64 v[28:29], 10, v[28:29]
	v_lshl_add_u64 v[28:29], s[20:21], 0, v[28:29]
	v_lshl_add_u64 v[28:29], v[28:29], 0, v[0:1]
	v_lshl_add_u64 v[28:29], v[28:29], 0, v[32:33]
	s_nop 0
	v_mfma_f32_32x32x16_bf16 v[8:23], v[2:5], v[58:61], v[8:23]
	ds_read_b128 v[2:5], v241 offset:8704
	ds_read_b128 v[146:149], v241 offset:8736
	ds_read_b128 v[142:145], v241 offset:8768
	ds_read_b128 v[138:141], v241 offset:8800
	ds_read_b128 v[130:133], v241 offset:8832
	ds_read_b128 v[126:129], v241 offset:8864
	ds_read_b128 v[134:137], v241 offset:8896
	s_nop 0
	ds_read_b128 v[28:31], v241 offset:8928
	s_nop 0
	v_mfma_f32_32x32x16_bf16 v[8:23], v[24:27], v[54:57], v[8:23]
	s_waitcnt vmcnt(16)
	v_lshrrev_b32_e32 v232, 4, v172
	v_and_b32_e32 v233, 15, v172
	v_mul_u32_u24_e32 v232, 0x110, v232
	v_lshl_add_u32 v232, v233, 4, v232
	v_add_u32_e32 v232, v232, v182
	v_mul_u32_u24_e32 v233, 0x110, v110
	v_add3_u32 v233, v233, v32, v182
	v_add_u32_e32 v232, 0x800, v232
	v_add_u32_e32 v233, 0x800, v233
	ds_write_b128 v232, v[200:203]
	ds_write_b128 v232, v[204:207] offset:4352
	ds_write_b128 v232, v[208:211] offset:8704
	ds_write_b128 v232, v[212:215] offset:13056
	ds_write_b128 v232, v[216:219] offset:17408
	ds_write_b128 v232, v[220:223] offset:21760
	ds_write_b128 v232, v[224:227] offset:26112
	ds_write_b128 v232, v[228:231] offset:30464
	s_waitcnt lgkmcnt(0)
	s_barrier
	ds_read_b128 v[24:27], v233
	ds_read_b128 v[122:125], v233 offset:32
	ds_read_b128 v[118:121], v233 offset:64
	ds_read_b128 v[114:117], v233 offset:96
	ds_read_b128 v[110:113], v233 offset:128
	ds_read_b128 v[46:49], v233 offset:160
	ds_read_b128 v[42:45], v233 offset:192
	ds_read_b128 v[38:41], v233 offset:224
	s_nop 0
	v_mfma_f32_32x32x16_bf16 v[8:23], v[150:153], v[50:53], v[8:23]
	v_min_u32_e32 v0, v171, v193
	v_max_u32_e32 v6, v171, v193
	v_sub_u32_e32 v0, v6, v0
	v_cvt_f32_u32_e32 v0, v0
	v_or_b32_e32 v6, 1, v171
	v_mul_f32_e32 v7, v194, v0
	v_cmp_gt_f32_e32 vcc, s34, v7
	s_nop 1
	v_cndmask_b32_e32 v7, 0, v187, vcc
	v_fmac_f32_e32 v7, v194, v0
	v_exp_f32_e32 v0, v7
	v_min_u32_e32 v7, v6, v193
	v_max_u32_e32 v6, v6, v193
	v_sub_u32_e32 v6, v6, v7
	v_cvt_f32_u32_e32 v7, v6
	v_cndmask_b32_e32 v6, 0, v188, vcc
	v_ldexp_f32 v6, v0, v6
	v_mul_f32_e32 v0, v194, v7
	v_cmp_gt_f32_e32 vcc, s34, v0
	s_nop 1
	v_cndmask_b32_e32 v0, 0, v187, vcc
	v_fmac_f32_e32 v0, v194, v7
	v_exp_f32_e32 v0, v0
	v_or_b32_e32 v7, 2, v171
	v_min_u32_e32 v150, v7, v193
	v_max_u32_e32 v7, v7, v193
	v_sub_u32_e32 v7, v7, v150
	v_cvt_f32_u32_e32 v152, v7
	v_cndmask_b32_e32 v7, 0, v188, vcc
	v_ldexp_f32 v7, v0, v7
	v_pk_mul_f32 v[150:151], v[8:9], v[6:7]
	v_or_b32_e32 v6, 3, v171
	v_min_u32_e32 v7, v6, v193
	v_max_u32_e32 v6, v6, v193
	v_sub_u32_e32 v6, v6, v7
	v_cvt_f32_u32_e32 v6, v6
	v_mul_f32_e32 v0, v194, v152
	v_cmp_gt_f32_e32 vcc, s34, v0
	v_mul_f32_e32 v8, v194, v6
	s_nop 0
	v_cndmask_b32_e32 v0, 0, v187, vcc
	v_cndmask_b32_e32 v7, 0, v188, vcc
	v_cmp_gt_f32_e32 vcc, s34, v8
	v_fmac_f32_e32 v0, v194, v152
	v_exp_f32_e32 v0, v0
	v_cndmask_b32_e32 v8, 0, v187, vcc
	v_fmac_f32_e32 v8, v194, v6
	v_or_b32_e32 v6, 8, v171
	v_min_u32_e32 v9, v6, v193
	v_max_u32_e32 v6, v6, v193
	v_sub_u32_e32 v6, v6, v9
	v_exp_f32_e32 v8, v8
	v_cvt_f32_u32_e32 v9, v6
	v_ldexp_f32 v6, v0, v7
	v_cndmask_b32_e32 v0, 0, v188, vcc
	v_ldexp_f32 v7, v8, v0
	v_mul_f32_e32 v0, v194, v9
	v_cmp_gt_f32_e32 vcc, s34, v0
	v_or_b32_e32 v8, 9, v171
	v_pk_mul_f32 v[152:153], v[10:11], v[6:7]
	v_cndmask_b32_e32 v0, 0, v187, vcc
	v_fmac_f32_e32 v0, v194, v9
	v_min_u32_e32 v9, v8, v193
	v_max_u32_e32 v8, v8, v193
	v_sub_u32_e32 v8, v8, v9
	v_exp_f32_e32 v0, v0
	v_cvt_f32_u32_e32 v8, v8
	v_cndmask_b32_e32 v6, 0, v188, vcc
	v_or_b32_e32 v7, 10, v171
	v_ldexp_f32 v6, v0, v6
	v_mul_f32_e32 v0, v194, v8
	v_cmp_gt_f32_e32 vcc, s34, v0
	s_nop 1
	v_cndmask_b32_e32 v0, 0, v187, vcc
	v_fmac_f32_e32 v0, v194, v8
	v_exp_f32_e32 v0, v0
	v_min_u32_e32 v8, v7, v193
	v_max_u32_e32 v7, v7, v193
	v_sub_u32_e32 v7, v7, v8
	v_cvt_f32_u32_e32 v8, v7
	v_cndmask_b32_e32 v7, 0, v188, vcc
	v_ldexp_f32 v7, v0, v7
	v_pk_mul_f32 v[156:157], v[12:13], v[6:7]
	v_or_b32_e32 v6, 11, v171
	v_min_u32_e32 v7, v6, v193
	v_max_u32_e32 v6, v6, v193
	v_sub_u32_e32 v6, v6, v7
	v_cvt_f32_u32_e32 v6, v6
	v_mul_f32_e32 v0, v194, v8
	v_cmp_gt_f32_e32 vcc, s34, v0
	s_nop 1
	v_cndmask_b32_e32 v0, 0, v187, vcc
	v_fmac_f32_e32 v0, v194, v8
	v_mul_f32_e32 v8, v194, v6
	v_cndmask_b32_e32 v7, 0, v188, vcc
	v_cmp_gt_f32_e32 vcc, s34, v8
	v_exp_f32_e32 v0, v0
	s_nop 0
	v_cndmask_b32_e32 v8, 0, v187, vcc
	v_fmac_f32_e32 v8, v194, v6
	v_or_b32_e32 v6, 16, v171
	v_min_u32_e32 v9, v6, v193
	v_max_u32_e32 v6, v6, v193
	v_sub_u32_e32 v6, v6, v9
	v_exp_f32_e32 v8, v8
	v_cvt_f32_u32_e32 v9, v6
	v_ldexp_f32 v6, v0, v7
	v_cndmask_b32_e32 v0, 0, v188, vcc
	v_ldexp_f32 v7, v8, v0
	v_mul_f32_e32 v0, v194, v9
	v_cmp_gt_f32_e32 vcc, s34, v0
	v_or_b32_e32 v8, 17, v171
	v_pk_mul_f32 v[158:159], v[14:15], v[6:7]
	v_cndmask_b32_e32 v0, 0, v187, vcc
	v_fmac_f32_e32 v0, v194, v9
	v_min_u32_e32 v9, v8, v193
	v_max_u32_e32 v8, v8, v193
	v_sub_u32_e32 v8, v8, v9
	v_exp_f32_e32 v0, v0
	v_cvt_f32_u32_e32 v8, v8
	v_cndmask_b32_e32 v6, 0, v188, vcc
	v_or_b32_e32 v7, 18, v171
	v_ldexp_f32 v6, v0, v6
	v_mul_f32_e32 v0, v194, v8
	v_cmp_gt_f32_e32 vcc, s34, v0
	s_nop 1
	v_cndmask_b32_e32 v0, 0, v187, vcc
	v_fmac_f32_e32 v0, v194, v8
	v_exp_f32_e32 v0, v0
	v_min_u32_e32 v8, v7, v193
	v_max_u32_e32 v7, v7, v193
	v_sub_u32_e32 v7, v7, v8
	v_cvt_f32_u32_e32 v8, v7
	v_cndmask_b32_e32 v7, 0, v188, vcc
	v_ldexp_f32 v7, v0, v7
	v_pk_mul_f32 v[160:161], v[16:17], v[6:7]
	v_or_b32_e32 v6, 19, v171
	v_min_u32_e32 v7, v6, v193
	v_max_u32_e32 v6, v6, v193
	v_sub_u32_e32 v6, v6, v7
	v_cvt_f32_u32_e32 v6, v6
	v_mul_f32_e32 v0, v194, v8
	v_cmp_gt_f32_e32 vcc, s34, v0
	s_nop 1
	v_cndmask_b32_e32 v0, 0, v187, vcc
	v_fmac_f32_e32 v0, v194, v8
	v_mul_f32_e32 v8, v194, v6
	v_cndmask_b32_e32 v7, 0, v188, vcc
	v_cmp_gt_f32_e32 vcc, s34, v8
	v_exp_f32_e32 v0, v0
	s_nop 0
	v_cndmask_b32_e32 v8, 0, v187, vcc
	v_fmac_f32_e32 v8, v194, v6
	v_exp_f32_e32 v6, v8
	v_or_b32_e32 v8, 24, v171
	v_min_u32_e32 v9, v8, v193
	v_max_u32_e32 v8, v8, v193
	v_sub_u32_e32 v8, v8, v9
	v_cvt_f32_u32_e32 v8, v8
	v_ldexp_f32 v176, v0, v7
	v_cndmask_b32_e32 v0, 0, v188, vcc
	v_ldexp_f32 v177, v6, v0
	v_mul_f32_e32 v0, v194, v8
	v_cmp_gt_f32_e32 vcc, s34, v0
	v_or_b32_e32 v6, 25, v171
	v_min_u32_e32 v7, v6, v193
	v_cndmask_b32_e32 v0, 0, v187, vcc
	v_max_u32_e32 v6, v6, v193
	v_fmac_f32_e32 v0, v194, v8
	v_sub_u32_e32 v178, v6, v7
	s_nop 0
	v_mfma_f32_32x32x16_bf16 v[2:17], v[2:5], v[78:81], 0
	v_exp_f32_e32 v0, v0
	v_cvt_f32_u32_e32 v178, v178
	v_pk_mul_f32 v[18:19], v[18:19], v[176:177]
	v_cndmask_b32_e32 v176, 0, v188, vcc
	v_ldexp_f32 v176, v0, v176
	v_mul_f32_e32 v0, v194, v178
	v_cmp_gt_f32_e32 vcc, s34, v0
	s_nop 0
	v_mfma_f32_32x32x16_bf16 v[2:17], v[146:149], v[74:77], v[2:17]
	v_or_b32_e32 v146, 26, v171
	v_cndmask_b32_e32 v0, 0, v187, vcc
	v_fmac_f32_e32 v0, v194, v178
	v_exp_f32_e32 v0, v0
	v_min_u32_e32 v147, v146, v193
	v_max_u32_e32 v146, v146, v193
	v_sub_u32_e32 v146, v146, v147
	s_nop 0
	v_mfma_f32_32x32x16_bf16 v[2:17], v[142:145], v[70:73], v[2:17]
	v_cndmask_b32_e32 v142, 0, v188, vcc
	v_ldexp_f32 v177, v0, v142
	v_or_b32_e32 v142, 27, v171
	v_min_u32_e32 v143, v142, v193
	v_max_u32_e32 v142, v142, v193
	v_cvt_f32_u32_e32 v146, v146
	v_pk_mul_f32 v[20:21], v[20:21], v[176:177]
	s_nop 0
	v_mfma_f32_32x32x16_bf16 v[2:17], v[138:141], v[66:69], v[2:17]
	v_sub_u32_e32 v138, v142, v143
	v_cvt_f32_u32_e32 v138, v138
	v_mul_f32_e32 v0, v194, v146
	v_cmp_gt_f32_e32 vcc, s34, v0
	v_mul_f32_e32 v139, v194, v138
	s_nop 0
	v_cndmask_b32_e32 v0, 0, v187, vcc
	s_nop 0
	v_mfma_f32_32x32x16_bf16 v[2:17], v[130:133], v[62:65], v[2:17]
	v_cmp_gt_f32_e64 s[0:1], s34, v139
	v_fmac_f32_e32 v0, v194, v146
	v_exp_f32_e32 v0, v0
	v_cndmask_b32_e64 v130, 0, v187, s[0:1]
	v_fmac_f32_e32 v130, v194, v138
	v_exp_f32_e32 v131, v130
	v_cndmask_b32_e32 v130, 0, v188, vcc
	v_ldexp_f32 v130, v0, v130
	v_cndmask_b32_e64 v0, 0, v188, s[0:1]
	v_ldexp_f32 v131, v131, v0
	v_or_b32_e32 v0, 32, v171
	s_nop 0
	v_mfma_f32_32x32x16_bf16 v[2:17], v[126:129], v[58:61], v[2:17]
	v_cvt_pk_bf16_f32 v127, v18, v19
	v_min_u32_e32 v18, v0, v193
	v_max_u32_e32 v0, v0, v193
	v_sub_u32_e32 v0, v0, v18
	v_cvt_f32_u32_e32 v0, v0
	v_or_b32_e32 v19, 33, v171
	v_cvt_pk_bf16_f32 v128, v20, v21
	v_min_u32_e32 v20, v19, v193
	v_max_u32_e32 v19, v19, v193
	v_sub_u32_e32 v19, v19, v20
	v_cvt_f32_u32_e32 v19, v19
	v_mul_f32_e32 v18, v194, v0
	v_cmp_gt_f32_e32 vcc, s34, v18
	s_nop 0
	v_mfma_f32_32x32x16_bf16 v[2:17], v[134:137], v[54:57], v[2:17]
	v_mul_f32_e32 v20, v194, v19
	v_cndmask_b32_e32 v18, 0, v187, vcc
	v_fmac_f32_e32 v18, v194, v0
	v_exp_f32_e32 v0, v18
	v_cndmask_b32_e32 v18, 0, v188, vcc
	v_cmp_gt_f32_e32 vcc, s34, v20
	v_pk_mul_f32 v[22:23], v[22:23], v[130:131]
	v_ldexp_f32 v18, v0, v18
	v_cndmask_b32_e32 v20, 0, v187, vcc
	v_fmac_f32_e32 v20, v194, v19
	v_exp_f32_e32 v19, v20
	v_or_b32_e32 v20, 34, v171
	v_min_u32_e32 v21, v20, v193
	v_max_u32_e32 v20, v20, v193
	v_sub_u32_e32 v20, v20, v21
	v_cvt_f32_u32_e32 v20, v20
	v_cndmask_b32_e32 v0, 0, v188, vcc
	v_ldexp_f32 v19, v19, v0
	ds_read2_b64 v[34:37], v242 offset1:2
	ds_read2_b64 v[106:109], v242 offset0:4 offset1:6
	ds_read2_b64 v[102:105], v242 offset0:8 offset1:10
	ds_read2_b64 v[98:101], v242 offset0:12 offset1:14
	ds_read2_b64 v[94:97], v243 offset1:2
	ds_read2_b64 v[90:93], v243 offset0:4 offset1:6
	ds_read2_b64 v[86:89], v243 offset0:8 offset1:10
	ds_read2_b64 v[82:85], v243 offset0:12 offset1:14
	v_mfma_f32_32x32x16_bf16 v[2:17], v[28:31], v[50:53], v[2:17]
	v_mul_f32_e32 v0, v194, v20
	v_cmp_gt_f32_e32 vcc, s34, v0
	v_cvt_pk_bf16_f32 v129, v22, v23
	v_cvt_pk_bf16_f32 v130, v150, v151
	v_cndmask_b32_e32 v0, 0, v187, vcc
	v_fmac_f32_e32 v0, v194, v20
	v_or_b32_e32 v20, 35, v171
	v_min_u32_e32 v21, v20, v193
	v_max_u32_e32 v20, v20, v193
	v_sub_u32_e32 v20, v20, v21
	v_exp_f32_e32 v0, v0
	v_cvt_f32_u32_e32 v20, v20
	v_pk_mul_f32 v[176:177], v[2:3], v[18:19]
	v_cndmask_b32_e32 v2, 0, v188, vcc
	v_ldexp_f32 v2, v0, v2
	v_mul_f32_e32 v0, v194, v20
	v_cmp_gt_f32_e32 vcc, s34, v0
	v_or_b32_e32 v3, 40, v171
	v_min_u32_e32 v18, v3, v193
	v_cndmask_b32_e32 v0, 0, v187, vcc
	v_fmac_f32_e32 v0, v194, v20
	v_exp_f32_e32 v0, v0
	v_max_u32_e32 v3, v3, v193
	v_sub_u32_e32 v3, v3, v18
	v_cvt_f32_u32_e32 v18, v3
	v_cndmask_b32_e32 v3, 0, v188, vcc
	v_ldexp_f32 v3, v0, v3
	v_pk_mul_f32 v[178:179], v[4:5], v[2:3]
	v_or_b32_e32 v2, 41, v171
	v_min_u32_e32 v3, v2, v193
	v_max_u32_e32 v2, v2, v193
	v_sub_u32_e32 v2, v2, v3
	v_cvt_f32_u32_e32 v2, v2
	v_mul_f32_e32 v0, v194, v18
	v_cmp_gt_f32_e32 vcc, s34, v0
	v_cvt_pk_bf16_f32 v131, v152, v153
	v_mul_f32_e32 v4, v194, v2
	v_cndmask_b32_e32 v0, 0, v187, vcc
	v_cndmask_b32_e32 v3, 0, v188, vcc
	v_cmp_gt_f32_e32 vcc, s34, v4
	v_fmac_f32_e32 v0, v194, v18
	v_exp_f32_e32 v0, v0
	v_cndmask_b32_e32 v4, 0, v187, vcc
	v_fmac_f32_e32 v4, v194, v2
	v_or_b32_e32 v2, 42, v171
	v_min_u32_e32 v5, v2, v193
	v_max_u32_e32 v2, v2, v193
	v_sub_u32_e32 v2, v2, v5
	v_exp_f32_e32 v4, v4
	v_cvt_f32_u32_e32 v5, v2
	v_ldexp_f32 v2, v0, v3
	v_cndmask_b32_e32 v0, 0, v188, vcc
	v_ldexp_f32 v3, v4, v0
	v_mul_f32_e32 v0, v194, v5
	v_cmp_gt_f32_e32 vcc, s34, v0
	v_or_b32_e32 v4, 43, v171
	v_pk_mul_f32 v[6:7], v[6:7], v[2:3]
	v_cndmask_b32_e32 v0, 0, v187, vcc
	v_fmac_f32_e32 v0, v194, v5
	v_min_u32_e32 v5, v4, v193
	v_max_u32_e32 v4, v4, v193
	v_sub_u32_e32 v4, v4, v5
	v_exp_f32_e32 v0, v0
	v_cvt_f32_u32_e32 v4, v4
	v_cndmask_b32_e32 v2, 0, v188, vcc
	v_or_b32_e32 v3, 48, v171
	v_ldexp_f32 v2, v0, v2
	v_mul_f32_e32 v0, v194, v4
	v_cmp_gt_f32_e32 vcc, s34, v0
	v_cvt_pk_bf16_f32 v132, v156, v157
	v_cvt_pk_bf16_f32 v133, v158, v159
	v_cndmask_b32_e32 v0, 0, v187, vcc
	v_fmac_f32_e32 v0, v194, v4
	v_exp_f32_e32 v0, v0
	v_min_u32_e32 v4, v3, v193
	v_max_u32_e32 v3, v3, v193
	v_sub_u32_e32 v3, v3, v4
	v_cvt_f32_u32_e32 v4, v3
	v_cndmask_b32_e32 v3, 0, v188, vcc
	v_ldexp_f32 v3, v0, v3
	v_pk_mul_f32 v[8:9], v[8:9], v[2:3]
	v_or_b32_e32 v2, 49, v171
	v_min_u32_e32 v3, v2, v193
	v_max_u32_e32 v2, v2, v193
	v_sub_u32_e32 v2, v2, v3
	v_cvt_f32_u32_e32 v2, v2
	v_mul_f32_e32 v0, v194, v4
	v_cmp_gt_f32_e32 vcc, s34, v0
	v_cvt_pk_bf16_f32 v126, v160, v161
	s_nop 0
	v_cndmask_b32_e32 v0, 0, v187, vcc
	v_fmac_f32_e32 v0, v194, v4
	v_mul_f32_e32 v4, v194, v2
	v_cndmask_b32_e32 v3, 0, v188, vcc
	v_cmp_gt_f32_e32 vcc, s34, v4
	v_exp_f32_e32 v0, v0
	s_nop 0
	v_cndmask_b32_e32 v4, 0, v187, vcc
	v_fmac_f32_e32 v4, v194, v2
	v_or_b32_e32 v2, 50, v171
	v_min_u32_e32 v5, v2, v193
	v_max_u32_e32 v2, v2, v193
	v_sub_u32_e32 v2, v2, v5
	v_exp_f32_e32 v4, v4
	v_cvt_f32_u32_e32 v5, v2
	v_ldexp_f32 v2, v0, v3
	v_cndmask_b32_e32 v0, 0, v188, vcc
	v_ldexp_f32 v3, v4, v0
	v_mul_f32_e32 v0, v194, v5
	v_cmp_gt_f32_e32 vcc, s34, v0
	v_or_b32_e32 v4, 51, v171
	v_pk_mul_f32 v[10:11], v[10:11], v[2:3]
	v_cndmask_b32_e32 v0, 0, v187, vcc
	v_fmac_f32_e32 v0, v194, v5
	v_exp_f32_e32 v0, v0
	v_min_u32_e32 v5, v4, v193
	v_max_u32_e32 v4, v4, v193
	v_cndmask_b32_e32 v2, 0, v188, vcc
	v_sub_u32_e32 v4, v4, v5
	v_ldexp_f32 v18, v0, v2
	v_or_b32_e32 v2, 56, v171
	v_cvt_f32_u32_e32 v4, v4
	v_min_u32_e32 v3, v2, v193
	v_max_u32_e32 v2, v2, v193
	v_sub_u32_e32 v2, v2, v3
	v_cvt_f32_u32_e32 v22, v2
	v_or_b32_e32 v2, v192, v195
	v_ashrrev_i32_e32 v3, 31, v2
	v_mul_f32_e32 v0, v194, v4
	v_lshlrev_b64 v[2:3], 8, v[2:3]
	v_cmp_gt_f32_e32 vcc, s34, v0
	v_lshl_add_u64 v[2:3], v[154:155], 0, v[2:3]
	v_lshl_add_u64 v[20:21], v[2:3], 0, v[32:33]
	v_cndmask_b32_e32 v0, 0, v187, vcc
	v_fmac_f32_e32 v0, v194, v4
	ds_read_b128 v[2:5], v233 offset:8704
	ds_read_b128 v[158:161], v233 offset:8736
	ds_read_b128 v[154:157], v233 offset:8768
	ds_read_b128 v[150:153], v233 offset:8800
	ds_read_b128 v[146:149], v233 offset:8832
	ds_read_b128 v[142:145], v233 offset:8864
	ds_read_b128 v[138:141], v233 offset:8896
	ds_read_b128 v[134:137], v233 offset:8928
	v_exp_f32_e32 v0, v0
	v_cndmask_b32_e32 v19, 0, v188, vcc
	v_ldexp_f32 v19, v0, v19
	v_mul_f32_e32 v0, v194, v22
	v_cmp_gt_f32_e32 vcc, s34, v0
	v_pk_mul_f32 v[12:13], v[12:13], v[18:19]
	v_or_b32_e32 v18, 57, v171
	v_cndmask_b32_e32 v0, 0, v187, vcc
	v_fmac_f32_e32 v0, v194, v22
	v_exp_f32_e32 v0, v0
	v_min_u32_e32 v19, v18, v193
	v_max_u32_e32 v18, v18, v193
	v_sub_u32_e32 v18, v18, v19
	v_cvt_f32_u32_e32 v195, v18
	v_cndmask_b32_e32 v18, 0, v188, vcc
	v_ldexp_f32 v196, v0, v18
	s_waitcnt lgkmcnt(8)
	v_mfma_f32_32x32x16_bf16 v[18:33], v[24:27], v[78:81], 0
	v_mul_f32_e32 v0, v194, v195
	v_cmp_gt_f32_e32 vcc, s34, v0
	s_nop 1
	v_cndmask_b32_e32 v0, 0, v187, vcc
	v_fmac_f32_e32 v0, v194, v195
	v_or_b32_e32 v195, 58, v171
	s_nop 0
	v_mfma_f32_32x32x16_bf16 v[18:33], v[122:125], v[74:77], v[18:33]
	v_min_u32_e32 v197, v195, v193
	v_max_u32_e32 v122, v195, v193
	v_sub_u32_e32 v122, v122, v197
	v_exp_f32_e32 v0, v0
	v_cvt_f32_u32_e32 v122, v122
	v_cndmask_b32_e32 v123, 0, v188, vcc
	v_ldexp_f32 v197, v0, v123
	s_nop 0
	v_mfma_f32_32x32x16_bf16 v[18:33], v[118:121], v[70:73], v[18:33]
	v_or_b32_e32 v118, 59, v171
	v_min_u32_e32 v119, v118, v193
	v_max_u32_e32 v118, v118, v193
	v_sub_u32_e32 v118, v118, v119
	v_cvt_f32_u32_e32 v118, v118
	v_mul_f32_e32 v0, v194, v122
	v_cmp_gt_f32_e32 vcc, s34, v0
	s_nop 0
	v_mfma_f32_32x32x16_bf16 v[18:33], v[114:117], v[66:69], v[18:33]
	v_mul_f32_e32 v114, v194, v118
	v_cndmask_b32_e32 v0, 0, v187, vcc
	v_cmp_gt_f32_e64 s[0:1], s34, v114
	v_fmac_f32_e32 v0, v194, v122
	v_exp_f32_e32 v0, v0
	v_cndmask_b32_e64 v114, 0, v187, s[0:1]
	v_fmac_f32_e32 v114, v194, v118
	s_nop 0
	v_mfma_f32_32x32x16_bf16 v[18:33], v[110:113], v[62:65], v[18:33]
	v_exp_f32_e32 v114, v114
	v_cndmask_b32_e32 v110, 0, v188, vcc
	v_ldexp_f32 v110, v0, v110
	v_cndmask_b32_e64 v0, 0, v188, s[0:1]
	v_ldexp_f32 v111, v114, v0
	v_add_u32_e32 v0, 1, v193
	v_cvt_f32_u32_e32 v0, v0
	s_nop 0
	v_mfma_f32_32x32x16_bf16 v[18:33], v[46:49], v[58:61], v[18:33]
	v_cvt_pk_bf16_f32 v116, v6, v7
	v_mul_f32_e64 v14, v14, v196
	v_mul_f32_e64 v15, v15, v197
	v_mul_f32_e32 v6, v194, v0
	v_cmp_gt_f32_e32 vcc, s34, v6
	v_pk_mul_f32 v[16:17], v[16:17], v[110:111]
	v_cvt_pk_bf16_f32 v114, v176, v177
	v_cndmask_b32_e32 v6, 0, v187, vcc
	s_nop 0
	v_mfma_f32_32x32x16_bf16 v[18:33], v[42:45], v[54:57], v[18:33]
	v_fmac_f32_e32 v6, v194, v0
	v_exp_f32_e32 v0, v6
	v_cndmask_b32_e32 v6, 0, v188, vcc
	v_cvt_pk_bf16_f32 v115, v178, v179
	v_cvt_pk_bf16_f32 v117, v8, v9
	v_ldexp_f32 v0, v0, v6
	v_cvt_pk_bf16_f32 v110, v10, v11
	s_nop 0
	v_mfma_f32_32x32x16_bf16 v[18:33], v[38:41], v[50:53], v[18:33]
	v_cvt_pk_bf16_f32 v111, v12, v13
	v_cvt_pk_bf16_f32 v112, v14, v15
	v_cvt_pk_bf16_f32 v113, v16, v17
	s_waitcnt lgkmcnt(7)
	v_mfma_f32_32x32x16_bf16 v[2:17], v[2:5], v[78:81], 0
	s_movk_i32 s0, 0xffe0
	v_cmp_eq_u32_e32 vcc, 0, v173
	s_barrier
	s_waitcnt lgkmcnt(6)
	v_mfma_f32_32x32x16_bf16 v[2:17], v[158:161], v[74:77], v[2:17]
	s_waitcnt lgkmcnt(5)
	v_mfma_f32_32x32x16_bf16 v[2:17], v[154:157], v[70:73], v[2:17]
	s_waitcnt lgkmcnt(4)
	v_mfma_f32_32x32x16_bf16 v[2:17], v[150:153], v[66:69], v[2:17]
	s_waitcnt lgkmcnt(3)
	v_mfma_f32_32x32x16_bf16 v[2:17], v[146:149], v[62:65], v[2:17]
	s_waitcnt lgkmcnt(2)
	v_mfma_f32_32x32x16_bf16 v[2:17], v[142:145], v[58:61], v[2:17]
	s_waitcnt lgkmcnt(1)
	v_mfma_f32_32x32x16_bf16 v[2:17], v[138:141], v[54:57], v[2:17]
	v_mfma_f32_32x32x16_bf16 v[34:49], v[34:37], v[130:133], 0
	s_waitcnt lgkmcnt(0)
	v_mfma_f32_32x32x16_bf16 v[2:17], v[134:137], v[50:53], v[2:17]
	v_mfma_f32_32x32x16_bf16 v[50:65], v[94:97], v[130:133], 0
	v_mfma_f32_32x32x16_bf16 v[34:49], v[106:109], v[126:129], v[34:49]
	v_mfma_f32_32x32x16_bf16 v[50:65], v[90:93], v[126:129], v[50:65]
	v_mfma_f32_32x32x16_bf16 v[34:49], v[102:105], v[114:117], v[34:49]
	v_mfma_f32_32x32x16_bf16 v[50:65], v[86:89], v[114:117], v[50:65]
	v_mfma_f32_32x32x16_bf16 v[34:49], v[98:101], v[110:113], v[34:49]
	v_mfma_f32_32x32x16_bf16 v[50:65], v[82:85], v[110:113], v[50:65]
	s_nop 10
	v_fma_f32 v66, v0, v18, v34
	v_fma_f32 v67, v0, v19, v35
	v_fma_f32 v68, v0, v20, v36
	v_fma_f32 v69, v0, v21, v37
	v_fma_f32 v70, v0, v22, v38
	v_fma_f32 v71, v0, v23, v39
	v_pk_fma_f32 v[38:39], v[0:1], v[24:25], v[40:41] op_sel_hi:[0,1,1]
	v_pk_fma_f32 v[24:25], v[0:1], v[30:31], v[46:47] op_sel_hi:[0,1,1]
	v_pk_mul_f32 v[30:31], v[66:67], v[66:67]
	v_pk_fma_f32 v[36:37], v[0:1], v[26:27], v[42:43] op_sel_hi:[0,1,1]
	v_pk_fma_f32 v[34:35], v[0:1], v[28:29], v[44:45] op_sel_hi:[0,1,1]
	v_pk_fma_f32 v[22:23], v[0:1], v[32:33], v[48:49] op_sel_hi:[0,1,1]
	v_pk_mul_f32 v[32:33], v[68:69], v[68:69]
	v_pk_fma_f32 v[28:29], v[0:1], v[2:3], v[50:51] op_sel_hi:[0,1,1]
	v_pk_fma_f32 v[26:27], v[0:1], v[4:5], v[52:53] op_sel_hi:[0,1,1]
	v_pk_fma_f32 v[20:21], v[0:1], v[6:7], v[54:55] op_sel_hi:[0,1,1]
	v_pk_fma_f32 v[18:19], v[0:1], v[8:9], v[56:57] op_sel_hi:[0,1,1]
	v_pk_fma_f32 v[8:9], v[0:1], v[10:11], v[58:59] op_sel_hi:[0,1,1]
	v_pk_fma_f32 v[6:7], v[0:1], v[12:13], v[60:61] op_sel_hi:[0,1,1]
	v_pk_fma_f32 v[4:5], v[0:1], v[14:15], v[62:63] op_sel_hi:[0,1,1]
	v_pk_fma_f32 v[2:3], v[0:1], v[16:17], v[64:65] op_sel_hi:[0,1,1]
	v_add_f32_e32 v0, v30, v31
	v_add_f32_e32 v0, v32, v0
	v_pk_mul_f32 v[40:41], v[70:71], v[70:71]
	v_add_f32_e32 v0, v33, v0
	v_add_f32_e32 v0, v40, v0
	v_pk_mul_f32 v[42:43], v[38:39], v[38:39]
	v_add_f32_e32 v0, v41, v0
	v_add_f32_e32 v0, v42, v0
	v_pk_mul_f32 v[44:45], v[36:37], v[36:37]
	v_add_f32_e32 v0, v43, v0
	v_add_f32_e32 v0, v44, v0
	v_pk_mul_f32 v[46:47], v[34:35], v[34:35]
	v_add_f32_e32 v0, v45, v0
	v_add_f32_e32 v0, v46, v0
	v_pk_mul_f32 v[48:49], v[24:25], v[24:25]
	v_add_f32_e32 v0, v47, v0
	v_add_f32_e32 v0, v48, v0
	v_pk_mul_f32 v[72:73], v[22:23], v[22:23]
	v_add_f32_e32 v0, v49, v0
	v_add_f32_e32 v0, v72, v0
	v_pk_mul_f32 v[50:51], v[28:29], v[28:29]
	v_add_f32_e32 v0, v73, v0
	v_add_f32_e32 v0, v50, v0
	v_pk_mul_f32 v[52:53], v[26:27], v[26:27]
	v_add_f32_e32 v0, v51, v0
	v_add_f32_e32 v0, v52, v0
	v_pk_mul_f32 v[54:55], v[20:21], v[20:21]
	v_add_f32_e32 v0, v53, v0
	v_add_f32_e32 v0, v54, v0
	v_pk_mul_f32 v[56:57], v[18:19], v[18:19]
	v_add_f32_e32 v0, v55, v0
	v_add_f32_e32 v0, v56, v0
	v_pk_mul_f32 v[10:11], v[8:9], v[8:9]
	v_add_f32_e32 v0, v57, v0
	v_add_f32_e32 v0, v10, v0
	v_pk_mul_f32 v[12:13], v[6:7], v[6:7]
	v_add_f32_e32 v0, v11, v0
	v_add_f32_e32 v0, v12, v0
	v_pk_mul_f32 v[14:15], v[4:5], v[4:5]
	v_add_f32_e32 v0, v13, v0
	v_add_f32_e32 v0, v14, v0
	v_pk_mul_f32 v[16:17], v[2:3], v[2:3]
	v_add_f32_e32 v0, v15, v0
	v_add_f32_e32 v0, v16, v0
	v_add_f32_e32 v0, v17, v0
	ds_bpermute_b32 v12, v234, v0
	v_bfi_b32 v10, s0, v191, v172
	v_lshl_add_u32 v11, v10, 2, v182
	s_and_saveexec_b64 s[0:1], vcc
	s_cbranch_execz .LBB0_871
	s_waitcnt lgkmcnt(0)
	v_add_f32_e32 v0, v0, v12
	ds_write_b32 v11, v0
	s_branch .LBB0_871
